# attention tile loop: K/V tile DMA issue moved into LDS-read shadows, V batch-1 fragment reads hoisted above softmax
# speedup vs baseline: 1.0138x; 1.0138x over previous
.LBB0_1117:
	s_waitcnt vmcnt(0)
	s_waitcnt lgkmcnt(0)
	s_barrier
	s_and_b32 s92, s70, 1
	s_add_i32 s70, s70, 1
	s_lshl_b32 s71, s92, 15
	v_add_u32_e32 v2, s71, v160
	v_add_u32_e32 v3, v2, v153
	v_add_u32_e32 v124, v2, v154
	v_add_u32_e32 v125, v2, v155
	v_add_u32_e32 v2, v2, v156
	ds_read_b128 v[84:87], v3
	ds_read_b128 v[88:91], v3 offset:2048
	ds_read_b128 v[92:95], v124
	ds_read_b128 v[96:99], v124 offset:2048
	ds_read_b128 v[100:103], v125
	ds_read_b128 v[104:107], v125 offset:2048
	ds_read_b128 v[108:111], v2
	ds_read_b128 v[112:115], v2 offset:2048
	ds_read_b128 v[116:119], v3 offset:16384
	ds_read_b128 v[166:169], v3 offset:18432
	ds_read_b128 v[120:123], v124 offset:16384
	ds_read_b128 v[170:173], v124 offset:18432
	ds_read_b128 v[174:177], v125 offset:16384
	ds_read_b128 v[178:181], v125 offset:18432
	ds_read_b128 v[182:185], v2 offset:16384
	ds_read_b128 v[186:189], v2 offset:18432
	s_cmp_lt_i32 s70, s69
	s_cbranch_scc0 .Latt_k_done
	s_xor_b32 s0, s71, 0x8000
	v_lshl_add_u64 v[128:129], s[52:53], 0, v[146:147]
	s_add_i32 s1, s79, s0
	v_lshl_add_u64 v[130:131], v[128:129], 0, s[20:21]
	s_mov_b32 m0, s1
	s_nop 0
	global_load_lds_dwordx4 v[130:131], off
	v_lshl_add_u64 v[130:131], v[128:129], 0, s[54:55]
	s_add_i32 m0, s1, 0x800
	s_nop 0
	global_load_lds_dwordx4 v[130:131], off
	v_lshl_add_u64 v[130:131], v[128:129], 0, s[56:57]
	s_add_i32 m0, s1, 0x4000
	v_lshl_add_u64 v[128:129], v[128:129], 0, s[58:59]
	global_load_lds_dwordx4 v[130:131], off
	s_add_i32 m0, s1, 0x4800
	s_nop 0
	global_load_lds_dwordx4 v[128:129], off
.Latt_k_done:
	s_waitcnt lgkmcnt(0)
	v_mfma_f32_16x16x32_bf16 v[84:87], v[84:87], v[4:7], 0
	v_mfma_f32_16x16x32_bf16 v[84:87], v[92:95], v[8:11], v[84:87]
	v_mfma_f32_16x16x32_bf16 v[84:87], v[100:103], v[12:15], v[84:87]
	v_mfma_f32_16x16x32_bf16 v[128:131], v[108:111], v[16:19], v[84:87]
	v_mfma_f32_16x16x32_bf16 v[84:87], v[88:91], v[4:7], 0
	v_mfma_f32_16x16x32_bf16 v[84:87], v[96:99], v[8:11], v[84:87]
	v_mfma_f32_16x16x32_bf16 v[84:87], v[104:107], v[12:15], v[84:87]
	v_mfma_f32_16x16x32_bf16 v[124:127], v[112:115], v[16:19], v[84:87]
	v_mfma_f32_16x16x32_bf16 v[84:87], v[116:119], v[4:7], 0
	v_mfma_f32_16x16x32_bf16 v[84:87], v[120:123], v[8:11], v[84:87]
	v_mfma_f32_16x16x32_bf16 v[84:87], v[174:177], v[12:15], v[84:87]
	v_mfma_f32_16x16x32_bf16 v[120:123], v[182:185], v[16:19], v[84:87]
	v_mfma_f32_16x16x32_bf16 v[84:87], v[166:169], v[4:7], 0
	v_mfma_f32_16x16x32_bf16 v[84:87], v[170:173], v[8:11], v[84:87]
	v_mfma_f32_16x16x32_bf16 v[84:87], v[178:181], v[12:15], v[84:87]
	v_mfma_f32_16x16x32_bf16 v[116:119], v[186:189], v[16:19], v[84:87]
	v_add_u32_e32 v2, s71, v157
	v_add_u32_e32 v3, v2, v158
	v_add_u32_e32 v145, v2, v159
	ds_read_b128 v[100:103], v3
	ds_read_b128 v[88:91], v3 offset:2048
	ds_read_b128 v[112:115], v145
	ds_read_b128 v[104:107], v145 offset:2048
	ds_read_b128 v[92:95], v3 offset:4096
	ds_read_b128 v[84:87], v3 offset:6144
	ds_read_b128 v[108:111], v145 offset:4096
	ds_read_b128 v[96:99], v145 offset:6144
	ds_read_b128 v[194:197], v3 offset:8192
	ds_read_b128 v[198:201], v3 offset:10240
	ds_read_b128 v[202:205], v145 offset:8192
	ds_read_b128 v[206:209], v145 offset:10240
	ds_read_b128 v[210:213], v3 offset:12288
	ds_read_b128 v[214:217], v3 offset:14336
	ds_read_b128 v[218:221], v145 offset:12288
	ds_read_b128 v[222:225], v145 offset:14336
	s_cmp_lt_i32 s70, s69
	s_cbranch_scc0 .Latt_v_done
	s_xor_b32 s0, s71, 0x8000
	v_lshl_add_u64 v[186:187], s[48:49], 0, v[148:149]
	s_add_i32 s0, s80, s0
	v_lshl_add_u64 v[188:189], v[186:187], 0, s[60:61]
	s_mov_b32 m0, s0
	s_nop 0
	global_load_lds_dwordx4 v[188:189], off
	v_lshl_add_u64 v[188:189], v[186:187], 0, s[62:63]
	s_add_i32 m0, s0, 0x2000
	s_nop 0
	global_load_lds_dwordx4 v[188:189], off
	v_lshl_add_u64 v[188:189], v[186:187], 0, s[64:65]
	s_add_i32 m0, s0, 0x4000
	v_lshl_add_u64 v[186:187], v[186:187], 0, s[66:67]
	global_load_lds_dwordx4 v[188:189], off
	s_add_i32 m0, s0, 0x6000
	s_nop 0
	global_load_lds_dwordx4 v[186:187], off
.Latt_v_done:
	s_cmpk_lt_i32 s50, 0xffa6
	s_cbranch_scc1 .LBB0_1123
	v_add_u32_e32 v2, s50, v161
	v_subrev_u32_e32 v166, 62, v2
	v_max_i32_e32 v166, 0xffffff40, v166
	v_lshl_add_u32 v167, v166, 2, s81
	v_subrev_u32_e32 v166, 61, v2
	v_max_i32_e32 v166, 0xffffff40, v166
	v_lshl_add_u32 v168, v166, 2, s81
	v_subrev_u32_e32 v166, 60, v2
	v_max_i32_e32 v166, 0xffffff40, v166
	v_subrev_u32_e32 v174, 30, v2
	v_lshl_add_u32 v169, v166, 2, s81
	v_subrev_u32_e32 v166, 59, v2
	v_max_i32_e32 v174, 0xffffff40, v174
	v_max_i32_e32 v166, 0xffffff40, v166
	v_lshl_add_u32 v175, v174, 2, s81
	v_subrev_u32_e32 v174, 29, v2
	v_lshl_add_u32 v170, v166, 2, s81
	v_subrev_u32_e32 v166, 58, v2
	v_max_i32_e32 v174, 0xffffff40, v174
	v_max_i32_e32 v166, 0xffffff40, v166
	v_lshl_add_u32 v176, v174, 2, s81
	v_subrev_u32_e32 v174, 28, v2
	v_lshl_add_u32 v171, v166, 2, s81
	v_subrev_u32_e32 v166, 57, v2
	v_max_i32_e32 v174, 0xffffff40, v174
	v_max_i32_e32 v166, 0xffffff40, v166
	v_lshl_add_u32 v177, v174, 2, s81
	v_subrev_u32_e32 v174, 27, v2
	v_subrev_u32_e32 v165, 63, v2
	v_lshl_add_u32 v172, v166, 2, s81
	v_subrev_u32_e32 v166, 56, v2
	v_max_i32_e32 v174, 0xffffff40, v174
	v_max_i32_e32 v165, 0xffffff40, v165
	v_max_i32_e32 v166, 0xffffff40, v166
	v_lshl_add_u32 v178, v174, 2, s81
	v_subrev_u32_e32 v174, 26, v2
	v_lshl_add_u32 v165, v165, 2, s81
	v_lshl_add_u32 v173, v166, 2, s81
	v_max_i32_e32 v174, 0xffffff40, v174
	ds_read_b32 v166, v165 offset:768
	ds_read_b32 v167, v167 offset:768
	ds_read_b32 v168, v168 offset:768
	ds_read_b32 v169, v169 offset:768
	ds_read_b32 v170, v170 offset:768
	ds_read_b32 v171, v171 offset:768
	ds_read_b32 v172, v172 offset:768
	ds_read_b32 v173, v173 offset:768
	v_subrev_u32_e32 v165, 31, v2
	v_lshl_add_u32 v179, v174, 2, s81
	v_subrev_u32_e32 v174, 25, v2
	v_max_i32_e32 v165, 0xffffff40, v165
	v_max_i32_e32 v174, 0xffffff40, v174
	v_subrev_u32_e32 v2, 24, v2
	v_lshl_add_u32 v165, v165, 2, s81
	v_lshl_add_u32 v180, v174, 2, s81
	v_max_i32_e32 v2, 0xffffff40, v2
	v_lshl_add_u32 v2, v2, 2, s81
	ds_read_b32 v174, v165 offset:768
	ds_read_b32 v175, v175 offset:768
	ds_read_b32 v176, v176 offset:768
	ds_read_b32 v177, v177 offset:768
	ds_read_b32 v178, v178 offset:768
	ds_read_b32 v179, v179 offset:768
	ds_read_b32 v180, v180 offset:768
	ds_read_b32 v181, v2 offset:768
	s_waitcnt lgkmcnt(0)
	v_pk_add_f32 v[130:131], v[130:131], v[168:169]
	v_pk_add_f32 v[128:129], v[128:129], v[166:167]
	v_pk_add_f32 v[126:127], v[126:127], v[172:173]
	v_pk_add_f32 v[124:125], v[124:125], v[170:171]
	v_pk_add_f32 v[122:123], v[122:123], v[176:177]
	v_pk_add_f32 v[120:121], v[120:121], v[174:175]
	v_pk_add_f32 v[118:119], v[118:119], v[180:181]
	v_pk_add_f32 v[116:117], v[116:117], v[178:179]

.LBB0_1126:
	v_sub_f32_e32 v128, v128, v143
	v_exp_f32_e32 v128, v128
	v_sub_f32_e32 v129, v129, v143
	v_exp_f32_e32 v129, v129
	v_sub_f32_e32 v130, v130, v143
	v_exp_f32_e32 v130, v130
	v_sub_f32_e32 v131, v131, v143
	v_exp_f32_e32 v131, v131
	v_sub_f32_e32 v124, v124, v143
	v_add_f32_e32 v165, 0, v128
	v_exp_f32_e32 v124, v124
	v_sub_f32_e32 v125, v125, v143
	v_add_f32_e32 v165, v129, v165
	v_exp_f32_e32 v125, v125
	v_sub_f32_e32 v126, v126, v143
	v_add_f32_e32 v165, v130, v165
	v_exp_f32_e32 v126, v126
	v_sub_f32_e32 v127, v127, v143
	v_add_f32_e32 v165, v131, v165
	v_exp_f32_e32 v127, v127
	v_sub_f32_e32 v120, v120, v143
	v_add_f32_e32 v165, v124, v165
	v_exp_f32_e32 v166, v120
	v_sub_f32_e32 v120, v121, v143
	v_add_f32_e32 v165, v125, v165
	v_exp_f32_e32 v167, v120
	v_sub_f32_e32 v120, v122, v143
	v_add_f32_e32 v165, v126, v165
	v_exp_f32_e32 v168, v120
	v_sub_f32_e32 v120, v123, v143
	v_add_f32_e32 v165, v127, v165
	v_exp_f32_e32 v123, v120
	v_sub_f32_e32 v116, v116, v143
	v_add_f32_e32 v120, v166, v165
	v_exp_f32_e32 v165, v116
	v_sub_f32_e32 v116, v117, v143
	v_add_f32_e32 v120, v167, v120
	v_exp_f32_e32 v117, v116
	v_sub_f32_e32 v116, v118, v143
	v_add_f32_e32 v120, v168, v120
	v_exp_f32_e32 v169, v116
	v_sub_f32_e32 v116, v119, v143
	v_add_f32_e32 v120, v123, v120
	v_exp_f32_e32 v170, v116
	v_add_f32_e32 v116, v165, v120
	v_add_f32_e32 v116, v117, v116
	v_add_f32_e32 v116, v169, v116
	v_add_f32_e32 v116, v170, v116
	v_fmac_f32_e32 v116, v1, v2
	v_cvt_pk_bf16_f32 v118, v128, v129
	v_cvt_pk_bf16_f32 v119, v130, v131
	v_cvt_pk_bf16_f32 v120, v124, v125
	v_cvt_pk_bf16_f32 v121, v126, v127
	v_cvt_pk_bf16_f32 v122, v166, v167
	v_cvt_pk_bf16_f32 v123, v168, v123
	v_cvt_pk_bf16_f32 v124, v165, v117
	v_cvt_pk_bf16_f32 v125, v169, v170
	s_waitcnt lgkmcnt(0)
	v_mfma_f32_16x16x32_bf16 v[80:83], v[100:103], v[118:121], v[80:83]
	v_mfma_f32_16x16x32_bf16 v[76:79], v[88:91], v[118:121], v[76:79]
	v_mfma_f32_16x16x32_bf16 v[72:75], v[92:95], v[118:121], v[72:75]
	v_mfma_f32_16x16x32_bf16 v[68:71], v[84:87], v[118:121], v[68:71]
	v_mfma_f32_16x16x32_bf16 v[80:83], v[112:115], v[122:125], v[80:83]
	v_mfma_f32_16x16x32_bf16 v[76:79], v[104:107], v[122:125], v[76:79]
	v_mfma_f32_16x16x32_bf16 v[72:75], v[108:111], v[122:125], v[72:75]
	v_mfma_f32_16x16x32_bf16 v[68:71], v[96:99], v[122:125], v[68:71]
	ds_read_b128 v[84:87], v3 offset:16384
	ds_read_b128 v[88:91], v3 offset:18432
	ds_read_b128 v[92:95], v145 offset:16384
	ds_read_b128 v[96:99], v145 offset:18432
	ds_read_b128 v[100:103], v3 offset:20480
	ds_read_b128 v[104:107], v3 offset:22528
	ds_read_b128 v[108:111], v145 offset:20480
	ds_read_b128 v[112:115], v145 offset:22528
	v_mfma_f32_16x16x32_bf16 v[64:67], v[194:197], v[118:121], v[64:67]
	v_mfma_f32_16x16x32_bf16 v[60:63], v[198:201], v[118:121], v[60:63]
	v_mfma_f32_16x16x32_bf16 v[56:59], v[210:213], v[118:121], v[56:59]
	v_mfma_f32_16x16x32_bf16 v[52:55], v[214:217], v[118:121], v[52:55]
	v_mfma_f32_16x16x32_bf16 v[64:67], v[202:205], v[122:125], v[64:67]
	v_mfma_f32_16x16x32_bf16 v[60:63], v[206:209], v[122:125], v[60:63]
	v_mfma_f32_16x16x32_bf16 v[56:59], v[218:221], v[122:125], v[56:59]
	v_mfma_f32_16x16x32_bf16 v[52:55], v[222:225], v[122:125], v[52:55]
	ds_read_b128 v[126:129], v3 offset:24576
	ds_read_b128 v[166:169], v3 offset:26624
	ds_read_b128 v[170:173], v145 offset:24576
	ds_read_b128 v[174:177], v145 offset:26624
	ds_read_b128 v[178:181], v3 offset:28672
	ds_read_b128 v[182:185], v3 offset:30720
	ds_read_b128 v[186:189], v145 offset:28672
	ds_read_b128 v[190:193], v145 offset:30720
	s_waitcnt lgkmcnt(0)
	v_mfma_f32_16x16x32_bf16 v[48:51], v[84:87], v[118:121], v[48:51]
	v_mfma_f32_16x16x32_bf16 v[44:47], v[88:91], v[118:121], v[44:47]
	v_mfma_f32_16x16x32_bf16 v[40:43], v[100:103], v[118:121], v[40:43]
	v_mfma_f32_16x16x32_bf16 v[36:39], v[104:107], v[118:121], v[36:39]
	v_mfma_f32_16x16x32_bf16 v[48:51], v[92:95], v[122:125], v[48:51]
	v_mfma_f32_16x16x32_bf16 v[44:47], v[96:99], v[122:125], v[44:47]
	v_mfma_f32_16x16x32_bf16 v[40:43], v[108:111], v[122:125], v[40:43]
	v_mfma_f32_16x16x32_bf16 v[36:39], v[112:115], v[122:125], v[36:39]
	v_mfma_f32_16x16x32_bf16 v[32:35], v[126:129], v[118:121], v[32:35]
	v_mfma_f32_16x16x32_bf16 v[28:31], v[166:169], v[118:121], v[28:31]
	v_mfma_f32_16x16x32_bf16 v[24:27], v[178:181], v[118:121], v[24:27]
	v_mfma_f32_16x16x32_bf16 v[20:23], v[182:185], v[118:121], v[20:23]
	v_mfma_f32_16x16x32_bf16 v[32:35], v[170:173], v[122:125], v[32:35]
	v_mfma_f32_16x16x32_bf16 v[28:31], v[174:177], v[122:125], v[28:31]
	v_mfma_f32_16x16x32_bf16 v[24:27], v[186:189], v[122:125], v[24:27]
	v_mfma_f32_16x16x32_bf16 v[20:23], v[190:193], v[122:125], v[20:23]
	s_add_i32 s50, s50, 64
	v_lshl_add_u64 v[148:149], v[148:149], 0, s[60:61]
	s_cmp_eq_u32 s69, s70
	v_lshl_add_u64 v[146:147], v[146:147], 0, s[20:21]
	s_cbranch_scc1 .LBB0_1129
	v_mov_b32_e32 v1, v116
	s_branch .LBB0_1117
